# cache policy: final RMSNorm output stores write-through (sc0 sc1) instead of nt; on top of v70
# baseline (speedup 1.0000x reference)
; __device__ __forceinline__ float bflo(unsigned w) { return __uint_as_float(w << 16); }
; __device__ __forceinline__ float bfhi(unsigned w) { return __uint_as_float(w & 0xffff0000u); }
; template <bool OUT_F32>
; __device__ __forceinline__ void norm_rows_from_bf16(const bf16_t* H, const float* gain, bf16_t* OB, float* OF, int gw, int NGW, int lane) {
;     for (int m = gw; m < NTOK; m += NGW) {
;         const u32x4* hr = (const u32x4*)(H + (size_t)m * DM) + lane;
;         u32x4 q[4]; float v[4][8]; float s = 0.f;
; #pragma unroll
;         for (int j = 0; j < 4; ++j) q[j] = __builtin_nontemporal_load(hr + 64 * j);
; #pragma unroll
;         for (int j = 0; j < 4; ++j) { v[j][0] = bflo(q[j].x); v[j][1] = bfhi(q[j].x); v[j][2] = bflo(q[j].y); v[j][3] = bfhi(q[j].y); v[j][4] = bflo(q[j].z); v[j][5] = bfhi(q[j].z); v[j][6] = bflo(q[j].w); v[j][7] = bfhi(q[j].w);
; #pragma unroll
;             for (int e = 0; e < 8; ++e) s += v[j][e] * v[j][e]; }
;         const float rstd = 1.0f / sqrtf(wave_sum(s) * (1.0f / DM) + 1e-6f);
.Lfn_enter:
	v_mov_b64_e32 v[24:25], v[128:129]
	v_mov_b64_e32 v[26:27], v[130:131]
	v_mov_b64_e32 v[28:29], v[132:133]
	v_mov_b64_e32 v[30:31], v[134:135]
	v_mov_b64_e32 v[32:33], v[136:137]
	v_mov_b64_e32 v[34:35], v[138:139]
	v_mov_b64_e32 v[36:37], v[140:141]
	v_mov_b64_e32 v[38:39], v[142:143]
	v_lshl_add_u64 v[48:49], s[4:5], 0, v[0:1]
	s_add_i32 s54, s54, s92
	s_cmpk_lt_i32 s54, 0x4000
	s_cselect_b32 s10, s2, 0
	s_cselect_b32 s11, s3, 0
	v_lshl_add_u64 v[12:13], v[12:13], 0, s[10:11]
	global_load_dwordx4 v[128:131], v[12:13], off offset:3072 nt
	global_load_dwordx4 v[132:135], v[12:13], off nt
	global_load_dwordx4 v[136:139], v[12:13], off offset:1024 nt
	global_load_dwordx4 v[140:143], v[12:13], off offset:2048 nt
	v_and_b32_e32 v14, 0xffff0000, v27
	v_lshlrev_b32_e32 v50, 16, v28
	v_and_b32_e32 v51, 0xffff0000, v28
	v_lshlrev_b32_e32 v15, 16, v27
	v_lshlrev_b32_e32 v28, 16, v29
	v_and_b32_e32 v29, 0xffff0000, v29
	v_lshlrev_b32_e32 v66, 16, v26
	v_and_b32_e32 v67, 0xffff0000, v26
	v_pk_mul_f32 v[26:27], v[50:51], v[50:51]
	v_pk_mul_f32 v[68:69], v[28:29], v[28:29]
	v_add_f32_e32 v26, v26, v27
	v_lshlrev_b32_e32 v52, 16, v30
	v_and_b32_e32 v53, 0xffff0000, v30
	v_add_f32_e32 v26, v68, v26
	v_pk_mul_f32 v[70:71], v[52:53], v[52:53]
	v_add_f32_e32 v26, v69, v26
	v_lshlrev_b32_e32 v30, 16, v31
	v_and_b32_e32 v31, 0xffff0000, v31
	v_add_f32_e32 v26, v70, v26
	v_pk_mul_f32 v[72:73], v[30:31], v[30:31]
	v_add_f32_e32 v26, v71, v26
	v_lshlrev_b32_e32 v54, 16, v32
	v_and_b32_e32 v55, 0xffff0000, v32
	v_add_f32_e32 v26, v72, v26
	v_pk_mul_f32 v[74:75], v[54:55], v[54:55]
	v_add_f32_e32 v26, v73, v26
	v_lshlrev_b32_e32 v32, 16, v33
	v_and_b32_e32 v33, 0xffff0000, v33
	v_add_f32_e32 v26, v74, v26
	v_pk_mul_f32 v[76:77], v[32:33], v[32:33]
	v_add_f32_e32 v26, v75, v26
	v_lshlrev_b32_e32 v56, 16, v34
	v_and_b32_e32 v57, 0xffff0000, v34
	v_add_f32_e32 v26, v76, v26
	v_pk_mul_f32 v[78:79], v[56:57], v[56:57]
	v_add_f32_e32 v26, v77, v26
	v_lshlrev_b32_e32 v34, 16, v35
	v_and_b32_e32 v35, 0xffff0000, v35
	v_add_f32_e32 v26, v78, v26
	v_pk_mul_f32 v[80:81], v[34:35], v[34:35]
	v_add_f32_e32 v26, v79, v26
	v_lshlrev_b32_e32 v58, 16, v36
	v_and_b32_e32 v59, 0xffff0000, v36
	v_add_f32_e32 v26, v80, v26
	v_pk_mul_f32 v[82:83], v[58:59], v[58:59]
	v_add_f32_e32 v26, v81, v26
	v_lshlrev_b32_e32 v36, 16, v37
	v_and_b32_e32 v37, 0xffff0000, v37
	v_add_f32_e32 v26, v82, v26
	v_pk_mul_f32 v[84:85], v[36:37], v[36:37]
	v_add_f32_e32 v26, v83, v26
	v_lshlrev_b32_e32 v60, 16, v38
	v_and_b32_e32 v61, 0xffff0000, v38
	v_add_f32_e32 v26, v84, v26
	v_pk_mul_f32 v[86:87], v[60:61], v[60:61]
	v_add_f32_e32 v26, v85, v26
	v_lshlrev_b32_e32 v38, 16, v39
	v_and_b32_e32 v39, 0xffff0000, v39
	v_add_f32_e32 v26, v86, v26
	v_pk_mul_f32 v[88:89], v[38:39], v[38:39]
	v_add_f32_e32 v26, v87, v26
	v_lshlrev_b32_e32 v62, 16, v24
	v_and_b32_e32 v63, 0xffff0000, v24
	v_add_f32_e32 v26, v88, v26
	v_pk_mul_f32 v[90:91], v[62:63], v[62:63]
	v_add_f32_e32 v26, v89, v26
	v_lshlrev_b32_e32 v64, 16, v25
	v_and_b32_e32 v65, 0xffff0000, v25
	v_add_f32_e32 v26, v90, v26
	v_pk_mul_f32 v[92:93], v[64:65], v[64:65]
	v_add_f32_e32 v26, v91, v26
	v_add_f32_e32 v26, v92, v26
	v_pk_mul_f32 v[94:95], v[66:67], v[66:67]
	v_add_f32_e32 v26, v93, v26
	v_add_f32_e32 v26, v94, v26
	v_pk_mul_f32 v[24:25], v[14:15], v[14:15]
	v_add_f32_e32 v26, v95, v26
	v_add_f32_e32 v25, v25, v26
	v_add_f32_e32 v24, v24, v25
	ds_bpermute_b32 v25, v16, v24
	s_waitcnt lgkmcnt(0)
	v_add_f32_e32 v24, v24, v25
	ds_bpermute_b32 v25, v17, v24
	s_waitcnt lgkmcnt(0)
	v_add_f32_e32 v24, v24, v25
	ds_bpermute_b32 v25, v18, v24
	s_waitcnt lgkmcnt(0)
; template <bool OUT_F32>
; __device__ __forceinline__ void norm_rows_from_bf16(const bf16_t* H, const float* gain, bf16_t* OB, float* OF, int gw, int NGW, int lane) {
;     ...
;         const float rstd = 1.0f / sqrtf(wave_sum(s) * (1.0f / DM) + 1e-6f);
; #pragma unroll
;         for (int j = 0; j < 4; ++j) {
;             const int c0 = 8 * (lane + 64 * j);
;             const f32x4 g0 = *(const f32x4*)(gain + c0), g1 = *(const f32x4*)(gain + c0 + 4);
;             const float o0 = v[j][0] * rstd * g0[0], o1 = v[j][1] * rstd * g0[1], o2 = v[j][2] * rstd * g0[2], o3 = v[j][3] * rstd * g0[3];
;             const float o4 = v[j][4] * rstd * g1[0], o5 = v[j][5] * rstd * g1[1], o6 = v[j][6] * rstd * g1[2], o7 = v[j][7] * rstd * g1[3];
;             if (OUT_F32) { float* op = OF + (size_t)m * DM + c0; __builtin_nontemporal_store((f32x4){o0, o1, o2, o3}, (f32x4*)op); __builtin_nontemporal_store((f32x4){o4, o5, o6, o7}, (f32x4*)(op + 4)); }
;             else { u32x4 w; w.x = pk2(o0, o1); w.y = pk2(o2, o3); w.z = pk2(o4, o5); w.w = pk2(o6, o7); *(u32x4*)(OB + (size_t)m * DM + c0) = w; }
;         }
	v_add_f32_e32 v24, v24, v25
	ds_bpermute_b32 v25, v19, v24
	s_waitcnt lgkmcnt(0)
	v_add_f32_e32 v24, v24, v25
	ds_bpermute_b32 v25, v20, v24
	s_waitcnt lgkmcnt(0)
	v_add_f32_e32 v24, v24, v25
	ds_bpermute_b32 v25, v21, v24
	s_waitcnt lgkmcnt(0)
	v_add_f32_e32 v24, v24, v25
	v_fmamk_f32 v24, v24, 0x3a000000, v22
	v_mul_f32_e32 v25, 0x4f800000, v24
	v_cmp_gt_f32_e32 vcc, s8, v24
	s_nop 1
	v_cndmask_b32_e32 v24, v24, v25, vcc
	v_sqrt_f32_e32 v25, v24
	s_nop 0
	v_add_u32_e32 v26, -1, v25
	v_add_u32_e32 v27, 1, v25
	v_fma_f32 v68, -v26, v25, v24
	v_fma_f32 v69, -v27, v25, v24
	v_cmp_ge_f32_e64 s[0:1], 0, v68
	s_nop 1
	v_cndmask_b32_e64 v25, v25, v26, s[0:1]
	v_cmp_lt_f32_e64 s[0:1], 0, v69
	s_nop 1
	v_cndmask_b32_e64 v25, v25, v27, s[0:1]
	v_mul_f32_e32 v26, 0x37800000, v25
	v_cndmask_b32_e32 v25, v25, v26, vcc
	v_cmp_class_f32_e32 vcc, v24, v23
	s_nop 1
	v_cndmask_b32_e32 v24, v25, v24, vcc
	v_div_scale_f32 v25, s[0:1], v24, v24, 1.0
	v_rcp_f32_e32 v27, v25
	v_div_scale_f32 v26, vcc, 1.0, v24, 1.0
	v_fma_f32 v68, -v25, v27, 1.0
	v_fmac_f32_e32 v27, v68, v27
	v_mul_f32_e32 v68, v26, v27
	v_fma_f32 v69, -v25, v68, v26
	v_fmac_f32_e32 v68, v69, v27
	v_fma_f32 v25, -v25, v68, v26
	v_div_fmas_f32 v25, v25, v27, v68
	v_div_fixup_f32 v68, v25, v24, 1.0
	v_pk_mul_f32 v[24:25], v[68:69], v[50:51] op_sel_hi:[0,1]
	v_pk_mul_f32 v[26:27], v[68:69], v[28:29] op_sel_hi:[0,1]
	v_pk_mul_f32 v[28:29], v[68:69], v[52:53] op_sel_hi:[0,1]
	v_pk_mul_f32 v[30:31], v[68:69], v[30:31] op_sel_hi:[0,1]
	v_pk_mul_f32 v[26:27], v[98:99], v[26:27]
	v_pk_mul_f32 v[24:25], v[96:97], v[24:25]
	v_pk_mul_f32 v[30:31], v[102:103], v[30:31]
	v_pk_mul_f32 v[28:29], v[100:101], v[28:29]
	global_store_dwordx4 v[48:49], v[24:27], off sc0 sc1
	global_store_dwordx4 v[48:49], v[28:31], off offset:16 sc0 sc1
	v_pk_mul_f32 v[32:33], v[68:69], v[32:33] op_sel_hi:[0,1]
	v_pk_mul_f32 v[40:41], v[68:69], v[54:55] op_sel_hi:[0,1]
	v_pk_mul_f32 v[34:35], v[68:69], v[34:35] op_sel_hi:[0,1]
	v_pk_mul_f32 v[42:43], v[68:69], v[56:57] op_sel_hi:[0,1]
	v_pk_mul_f32 v[38:39], v[68:69], v[38:39] op_sel_hi:[0,1]
	v_pk_mul_f32 v[14:15], v[68:69], v[14:15] op_sel_hi:[0,1]
	v_pk_mul_f32 v[24:25], v[104:105], v[40:41]
	v_pk_mul_f32 v[26:27], v[106:107], v[32:33]
	v_pk_mul_f32 v[28:29], v[108:109], v[42:43]
	v_pk_mul_f32 v[30:31], v[110:111], v[34:35]
	global_store_dwordx4 v[48:49], v[24:27], off offset:2048 sc0 sc1
	global_store_dwordx4 v[48:49], v[28:31], off offset:2064 sc0 sc1
	v_pk_mul_f32 v[34:35], v[68:69], v[36:37] op_sel_hi:[0,1]
	v_pk_mul_f32 v[36:37], v[68:69], v[58:59] op_sel_hi:[0,1]
	v_lshl_add_u64 v[32:33], s[4:5], 0, v[4:5]
	v_pk_mul_f32 v[40:41], v[68:69], v[60:61] op_sel_hi:[0,1]
	v_pk_mul_f32 v[24:25], v[112:113], v[36:37]
	v_pk_mul_f32 v[26:27], v[114:115], v[34:35]
	v_pk_mul_f32 v[28:29], v[116:117], v[40:41]
	v_pk_mul_f32 v[30:31], v[118:119], v[38:39]
	global_store_dwordx4 v[32:33], v[24:27], off sc0 sc1
	global_store_dwordx4 v[32:33], v[28:31], off offset:16 sc0 sc1
	v_lshl_add_u64 v[32:33], s[4:5], 0, v[8:9]
	s_add_u32 s4, s4, s6
	s_addc_u32 s5, s5, s7
	v_pk_mul_f32 v[36:37], v[68:69], v[64:65] op_sel_hi:[0,1]
	v_pk_mul_f32 v[38:39], v[68:69], v[62:63] op_sel_hi:[0,1]
	s_cmpk_lt_i32 s54, 0x4000
	v_pk_mul_f32 v[34:35], v[68:69], v[66:67] op_sel_hi:[0,1]
	v_pk_mul_f32 v[24:25], v[120:121], v[38:39]
	v_pk_mul_f32 v[26:27], v[122:123], v[36:37]
	v_pk_mul_f32 v[28:29], v[124:125], v[34:35]
	v_pk_mul_f32 v[30:31], v[126:127], v[14:15] op_sel:[0,1] op_sel_hi:[1,0]
	global_store_dwordx4 v[32:33], v[24:27], off sc0 sc1
	global_store_dwordx4 v[32:33], v[28:31], off offset:16 sc0 sc1
	s_cbranch_scc1 .LBB0_955
